# layer-1 in-projection skew for the 5-tile workgroups reduced from 4 to 3 sleep quanta
# speedup vs baseline: 1.0016x; 1.0016x over previous
.Lcw_sleep:
	s_sleep 0x7f
	s_sleep 0x7f
	s_sleep 0x7f
.LBB0_243:
	s_add_u32 s16, s96, s0
	s_addc_u32 s17, s97, s1
	s_add_u32 s26, s16, 0xb000000
	v_readlane_b32 s2, v253, 28
	s_addc_u32 s27, s17, 0
	v_readlane_b32 s3, v253, 29
	s_add_u32 s28, s16, 0xf000000
	v_mov_b32_e32 v8, v197
	v_cndmask_b32_e64 v0, 0, 1, s[2:3]
	s_addc_u32 s29, s17, 0
	s_barrier
	v_cmp_ne_u32_e64 s[0:1], 1, v0
	s_andn2_b64 vcc, exec, s[2:3]
	v_readfirstlane_b32 s30, v8
	s_cbranch_vccnz .LBB0_245
	v_readlane_b32 s2, v253, 31
	s_add_u32 s8, s26, s2
	s_addc_u32 s9, s27, 0
	v_readlane_b32 s2, v253, 33
	s_add_u32 s10, s28, s2
	s_addc_u32 s11, s29, 0
	v_readlane_b32 s35, v253, 30
	v_readlane_b32 s3, v253, 32
